# t1 + modulate0 row loop: all 16 row loads of an iteration issued up front, fp16-copy stores under counted vmcnt(15/7) instead of load-wait0-store serialization
# speedup vs baseline: 1.0074x; 1.0018x over previous
.LBB0_202:
	v_lshlrev_b32_e32 v84, 2, v64
	global_load_dwordx4 v[60:63], v84, s[4:5]
	global_load_dwordx4 v[56:59], v84, s[4:5] offset:1024
	global_load_dwordx4 v[52:55], v84, s[4:5] offset:2048
	global_load_dwordx4 v[48:51], v84, s[4:5] offset:3072
	global_load_dwordx4 v[44:47], v78, s[4:5]
	global_load_dwordx4 v[40:43], v79, s[4:5]
	global_load_dwordx4 v[36:39], v80, s[4:5]
	global_load_dwordx4 v[32:35], v81, s[4:5]
	s_lshl_b64 s[22:23], s[22:23], 12
	v_lshl_add_u64 v[86:87], v[66:67], 0, s[22:23]
	s_add_i32 s22, s88, s20
	s_cmpk_lt_i32 s22, 0x4400
	s_cselect_b64 s[24:25], -1, 0
	s_cmpk_gt_i32 s22, 0x43ff
	s_cbranch_scc1 .Lmod0_one
	s_cmpk_lt_i32 s22, 0x4000
	s_mov_b64 s[26:27], -1
	s_cbranch_scc1 .LBB0_205
	s_load_dwordx2 s[4:5], s[6:7], 0x10
	s_add_i32 s8, s22, 0xffffc000
	s_lshl_b64 s[26:27], s[8:9], 13
	s_mov_b32 s23, s9
	s_waitcnt lgkmcnt(0)
	s_add_u32 s4, s4, s26
	s_addc_u32 s5, s5, s27
	s_mov_b64 s[26:27], 0

.LBB0_207:
	global_load_dwordx4 v[0:3], v84, s[4:5]
	global_load_dwordx4 v[4:7], v84, s[4:5] offset:1024
	global_load_dwordx4 v[8:11], v84, s[4:5] offset:2048
	global_load_dwordx4 v[12:15], v84, s[4:5] offset:3072
	global_load_dwordx4 v[16:19], v78, s[4:5]
	global_load_dwordx4 v[20:23], v79, s[4:5]
	global_load_dwordx4 v[24:27], v80, s[4:5]
	global_load_dwordx4 v[28:31], v81, s[4:5]
	s_lshl_b64 s[26:27], s[22:23], 12
	v_lshl_add_u64 v[104:105], v[66:67], 0, s[26:27]
	s_waitcnt vmcnt(15)
	v_cvt_pk_f16_f32 v89, v62, v63
	v_cvt_pk_f16_f32 v88, v60, v61
	global_store_dwordx2 v[86:87], v[88:89], off
	s_waitcnt vmcnt(15)
	v_cvt_pk_f16_f32 v107, v58, v59
	v_cvt_pk_f16_f32 v106, v56, v57
	global_store_dwordx2 v[86:87], v[106:107], off offset:512
	s_waitcnt vmcnt(15)
	v_cvt_pk_f16_f32 v89, v54, v55
	v_cvt_pk_f16_f32 v88, v52, v53
	global_store_dwordx2 v[86:87], v[88:89], off offset:1024
	s_waitcnt vmcnt(15)
	v_cvt_pk_f16_f32 v107, v50, v51
	v_cvt_pk_f16_f32 v106, v48, v49
	global_store_dwordx2 v[86:87], v[106:107], off offset:1536
	s_waitcnt vmcnt(15)
	v_cvt_pk_f16_f32 v89, v46, v47
	v_cvt_pk_f16_f32 v88, v44, v45
	global_store_dwordx2 v[86:87], v[88:89], off offset:2048
	s_waitcnt vmcnt(15)
	v_cvt_pk_f16_f32 v107, v42, v43
	v_cvt_pk_f16_f32 v106, v40, v41
	global_store_dwordx2 v[86:87], v[106:107], off offset:2560
	s_waitcnt vmcnt(15)
	v_cvt_pk_f16_f32 v89, v38, v39
	v_cvt_pk_f16_f32 v88, v36, v37
	global_store_dwordx2 v[86:87], v[88:89], off offset:3072
	s_waitcnt vmcnt(15)
	v_cvt_pk_f16_f32 v107, v34, v35
	v_cvt_pk_f16_f32 v106, v32, v33
	global_store_dwordx2 v[86:87], v[106:107], off offset:3584
	s_waitcnt vmcnt(15)
	v_cvt_pk_f16_f32 v89, v2, v3
	v_cvt_pk_f16_f32 v88, v0, v1
	global_store_dwordx2 v[104:105], v[88:89], off
	s_waitcnt vmcnt(15)
	v_cvt_pk_f16_f32 v107, v6, v7
	v_cvt_pk_f16_f32 v106, v4, v5
	global_store_dwordx2 v[104:105], v[106:107], off offset:512
	s_waitcnt vmcnt(15)
	v_cvt_pk_f16_f32 v89, v10, v11
	v_cvt_pk_f16_f32 v88, v8, v9
	global_store_dwordx2 v[104:105], v[88:89], off offset:1024
	s_waitcnt vmcnt(15)
	v_cvt_pk_f16_f32 v107, v14, v15
	v_cvt_pk_f16_f32 v106, v12, v13
	global_store_dwordx2 v[104:105], v[106:107], off offset:1536
	s_waitcnt vmcnt(15)
	v_cvt_pk_f16_f32 v89, v18, v19
	v_cvt_pk_f16_f32 v88, v16, v17
	global_store_dwordx2 v[104:105], v[88:89], off offset:2048
	s_waitcnt vmcnt(15)
	v_cvt_pk_f16_f32 v107, v22, v23
	v_cvt_pk_f16_f32 v106, v20, v21
	global_store_dwordx2 v[104:105], v[106:107], off offset:2560
	s_waitcnt vmcnt(15)
	v_cvt_pk_f16_f32 v89, v26, v27
	v_cvt_pk_f16_f32 v88, v24, v25
	global_store_dwordx2 v[104:105], v[88:89], off offset:3072
	s_waitcnt vmcnt(15)
	v_cvt_pk_f16_f32 v107, v30, v31
	v_cvt_pk_f16_f32 v106, v28, v29
	global_store_dwordx2 v[104:105], v[106:107], off offset:3584
	s_branch .LBB0_208
.Lmod0_one:
	s_waitcnt vmcnt(7)
	v_cvt_pk_f16_f32 v89, v62, v63
	v_cvt_pk_f16_f32 v88, v60, v61
	global_store_dwordx2 v[86:87], v[88:89], off
	s_waitcnt vmcnt(7)
	v_cvt_pk_f16_f32 v107, v58, v59
	v_cvt_pk_f16_f32 v106, v56, v57
	global_store_dwordx2 v[86:87], v[106:107], off offset:512
	s_waitcnt vmcnt(7)
	v_cvt_pk_f16_f32 v89, v54, v55
	v_cvt_pk_f16_f32 v88, v52, v53
	global_store_dwordx2 v[86:87], v[88:89], off offset:1024
	s_waitcnt vmcnt(7)
	v_cvt_pk_f16_f32 v107, v50, v51
	v_cvt_pk_f16_f32 v106, v48, v49
	global_store_dwordx2 v[86:87], v[106:107], off offset:1536
	s_waitcnt vmcnt(7)
	v_cvt_pk_f16_f32 v89, v46, v47
	v_cvt_pk_f16_f32 v88, v44, v45
	global_store_dwordx2 v[86:87], v[88:89], off offset:2048
	s_waitcnt vmcnt(7)
	v_cvt_pk_f16_f32 v107, v42, v43
	v_cvt_pk_f16_f32 v106, v40, v41
	global_store_dwordx2 v[86:87], v[106:107], off offset:2560
	s_waitcnt vmcnt(7)
	v_cvt_pk_f16_f32 v89, v38, v39
	v_cvt_pk_f16_f32 v88, v36, v37
	global_store_dwordx2 v[86:87], v[88:89], off offset:3072
	s_waitcnt vmcnt(7)
	v_cvt_pk_f16_f32 v107, v34, v35
	v_cvt_pk_f16_f32 v106, v32, v33
	global_store_dwordx2 v[86:87], v[106:107], off offset:3584
